# NSA sel/window loops: next-tile LDS write block moved from the step end to before the 2nd half-tile V reads (ds_write latency under the PV MFMAs), on top of v21
# baseline (speedup 1.0000x reference)
; #define TIDX opaque_tid()
; __device__ __forceinline__ unsigned pk2(float lo, float hi) { const f32x2v v = {lo, hi}; const bf16x2v r = __builtin_convertvector(v, bf16x2v); return __builtin_bit_cast(unsigned, r); }
; __device__ __forceinline__ f32x4 mfma16(bf16x8 a, bf16x8 b, f32x4 c) { return __builtin_amdgcn_mfma_f32_16x16x32_bf16(a, b, c, 0, 0, 0); }
; __device__ __forceinline__ void kv_lwrite(const KVRegs& r, char* lds, int buf) {
;   const int tid = TIDX, row = tid >> 3, cq = tid & 7;
;   char* kt = lds + NSA_KT + buf * 8192 + row * 128;
;   *(u32x4*)(kt + ((cq ^ (row & 7)) << 4)) = r.k0;
;   bf16_t* vt = (bf16_t*)(lds + NSA_VT + buf * 8704) + (cq * 8) * 68 + row;
; #pragma unroll
;   for (int i = 0; i < 4; ++i) { vt[(2 * i) * 68] = (bf16_t)(r.v0[i] & 0xffffu); vt[(2 * i + 1) * 68] = (bf16_t)(r.v0[i] >> 16); }
; }
; template <int MODE>
; __device__ __forceinline__ void nsa_compute(int cur, int buf, int t, int hl, u64 mymask, const bf16x8 (&Qf)[2][2], f32x4 (&O)[4][2], float (&m)[2], float (&l)[2],
;                                             const float (&inv)[2], float* impw, char* lds) {
;     ...
;           for (int e = 0; e < 4; ++e) { pv[kk][e] = __builtin_amdgcn_exp2f(sv[kk][e] - me); ps += pv[kk][e]; }
;         l[r] += ps;
;       }
;       if (MODE != 0) {
;         const unsigned w0 = pk2(pv[0][0], pv[0][1]), w1 = pk2(pv[0][2], pv[0][3]), w2 = pk2(pv[1][0], pv[1][1]), w3 = pk2(pv[1][2], pv[1][3]);
;         u32x4 pw; pw.x = w0; pw.y = w1; pw.z = w2; pw.w = w3;
;         Pf[r] = __builtin_bit_cast(bf16x8, pw);
;       }
;     }
;     if (MODE != 0) {
;       bf16x8 vfr[4];
; #pragma unroll
;       for (int df = 0; df < 4; ++df) {
;         const bf16x4 va = *(const bf16x4*)(vt + (df * 16 + fr) * 68 + 32 * s2 + 4 * fq);
;         const bf16x4 vb = *(const bf16x4*)(vt + (df * 16 + fr) * 68 + 32 * s2 + 16 + 4 * fq);
;         bf16x8 vf; vf[0] = va[0]; vf[1] = va[1]; vf[2] = va[2]; vf[3] = va[3]; vf[4] = vb[0]; vf[5] = vb[1]; vf[6] = vb[2]; vf[7] = vb[3];
;         vfr[df] = vf;
;       }
;       __builtin_amdgcn_s_setprio(1);
; #pragma unroll
;       for (int df = 0; df < 4; ++df)
; #pragma unroll
;         for (int r = 0; r < 2; ++r) O[df][r] = mfma16(vfr[df], Pf[r], O[df][r]);
;       __builtin_amdgcn_s_setprio(0);
.LBB0_373:
	v_sub_f32_e32 v91, v113, v90
	v_exp_f32_e32 v113, v91
	v_sub_f32_e32 v91, v112, v90
	v_exp_f32_e32 v112, v91
	v_sub_f32_e32 v91, v101, v90
	v_cvt_pk_bf16_f32 v124, v119, v114
	v_exp_f32_e32 v114, v91
	v_sub_f32_e32 v91, v100, v90
	v_cvt_pk_bf16_f32 v122, v115, v117
	v_exp_f32_e32 v115, v91
	v_sub_f32_e32 v91, v103, v90
	v_cvt_pk_bf16_f32 v123, v118, v116
	v_exp_f32_e32 v116, v91
	v_sub_f32_e32 v91, v102, v90
	s_xor_b32 s46, s46, 1
	s_cmp_lt_i32 s16, 0
	s_cbranch_scc1 .Lmy_lw_0
	v_mov_b32 v168, v179
	s_lshl_b32 s17, s46, 13
	v_ashrrev_i32_e32 v169, 3, v168
	v_xor_b32_e32 v171, v169, v168
	v_lshl_add_u32 v170, v169, 7, s17
	v_lshlrev_b32_e32 v171, 4, v171
	s_movk_i32 s30, 0x70
	v_lshlrev_b32_e32 v168, 3, v168
	v_and_or_b32 v170, v171, s30, v170
	s_lshl_b32 s30, s46, 9
	v_and_b32_e32 v168, 56, v168
	s_add_i32 s17, s17, s30
	v_mul_u32_u24_e32 v168, 0x88, v168
	v_lshlrev_b32_e32 v169, 1, v169
	v_add3_u32 v168, s17, v168, v169
	s_waitcnt vmcnt(1)
	ds_write_b128 v170, v[56:59]
	s_waitcnt vmcnt(0)
	ds_write_b16 v168, v60 offset:16384
	ds_write_b16_d16_hi v168, v60 offset:16520
	ds_write_b16 v168, v61 offset:16656
	ds_write_b16_d16_hi v168, v61 offset:16792
	ds_write_b16 v168, v62 offset:16928
	ds_write_b16_d16_hi v168, v62 offset:17064
	ds_write_b16 v168, v63 offset:17200
	ds_write_b16_d16_hi v168, v63 offset:17336
.Lmy_lw_0:
	ds_read2_b64 v[100:103], v137 offset0:8 offset1:12
	ds_read2_b64 v[126:129], v138 offset0:24 offset1:28
	ds_read2_b64 v[130:133], v139 offset0:40 offset1:44
	ds_read2_b64 v[134:137], v140 offset0:56 offset1:60
	v_sub_f32_e32 v89, v89, v90
	v_sub_f32_e32 v88, v88, v90
	v_exp_f32_e32 v117, v91
	v_exp_f32_e32 v118, v89
	v_exp_f32_e32 v119, v88
	v_cvt_pk_bf16_f32 v125, v121, v120
	v_cvt_pk_bf16_f32 v138, v113, v112
	v_cvt_pk_bf16_f32 v139, v114, v115
	v_cvt_pk_bf16_f32 v140, v116, v117
	v_cvt_pk_bf16_f32 v141, v118, v119
	s_setprio 1
	s_waitcnt lgkmcnt(3)
	v_mfma_f32_16x16x32_bf16 v[88:91], v[100:103], v[122:125], v[84:87]
	v_mfma_f32_16x16x32_bf16 v[96:99], v[100:103], v[138:141], v[96:99]
	s_waitcnt lgkmcnt(2)
	v_mfma_f32_16x16x32_bf16 v[100:103], v[126:129], v[122:125], v[80:83]
	v_mfma_f32_16x16x32_bf16 v[84:87], v[126:129], v[138:141], v[92:95]
	s_waitcnt lgkmcnt(1)
	v_mfma_f32_16x16x32_bf16 v[92:95], v[130:133], v[122:125], v[76:79]
	v_mfma_f32_16x16x32_bf16 v[76:79], v[130:133], v[138:141], v[108:111]
	s_waitcnt lgkmcnt(0)
	v_mfma_f32_16x16x32_bf16 v[80:83], v[134:137], v[122:125], v[72:75]
	v_mfma_f32_16x16x32_bf16 v[72:75], v[134:137], v[138:141], v[104:107]
	s_setprio 0

; #define TIDX opaque_tid()
; __device__ __forceinline__ unsigned pk2(float lo, float hi) { const f32x2v v = {lo, hi}; const bf16x2v r = __builtin_convertvector(v, bf16x2v); return __builtin_bit_cast(unsigned, r); }
; __device__ __forceinline__ f32x4 mfma16(bf16x8 a, bf16x8 b, f32x4 c) { return __builtin_amdgcn_mfma_f32_16x16x32_bf16(a, b, c, 0, 0, 0); }
; __device__ __forceinline__ void kv_lwrite(const KVRegs& r, char* lds, int buf) {
;   const int tid = TIDX, row = tid >> 3, cq = tid & 7;
;   char* kt = lds + NSA_KT + buf * 8192 + row * 128;
;   *(u32x4*)(kt + ((cq ^ (row & 7)) << 4)) = r.k0;
;   bf16_t* vt = (bf16_t*)(lds + NSA_VT + buf * 8704) + (cq * 8) * 68 + row;
; #pragma unroll
;   for (int i = 0; i < 4; ++i) { vt[(2 * i) * 68] = (bf16_t)(r.v0[i] & 0xffffu); vt[(2 * i + 1) * 68] = (bf16_t)(r.v0[i] >> 16); }
; }
; template <int MODE>
; __device__ __forceinline__ void nsa_compute(int cur, int buf, int t, int hl, u64 mymask, const bf16x8 (&Qf)[2][2], f32x4 (&O)[4][2], float (&m)[2], float (&l)[2],
;                                             const float (&inv)[2], float* impw, char* lds) {
;     ...
;           for (int e = 0; e < 4; ++e) { pv[kk][e] = __builtin_amdgcn_exp2f(sv[kk][e] - me); ps += pv[kk][e]; }
;         l[r] += ps;
;       }
;       if (MODE != 0) {
;         const unsigned w0 = pk2(pv[0][0], pv[0][1]), w1 = pk2(pv[0][2], pv[0][3]), w2 = pk2(pv[1][0], pv[1][1]), w3 = pk2(pv[1][2], pv[1][3]);
;         u32x4 pw; pw.x = w0; pw.y = w1; pw.z = w2; pw.w = w3;
;         Pf[r] = __builtin_bit_cast(bf16x8, pw);
;       }
;     }
;     if (MODE != 0) {
;       bf16x8 vfr[4];
; #pragma unroll
;       for (int df = 0; df < 4; ++df) {
;         const bf16x4 va = *(const bf16x4*)(vt + (df * 16 + fr) * 68 + 32 * s2 + 4 * fq);
;         const bf16x4 vb = *(const bf16x4*)(vt + (df * 16 + fr) * 68 + 32 * s2 + 16 + 4 * fq);
;         bf16x8 vf; vf[0] = va[0]; vf[1] = va[1]; vf[2] = va[2]; vf[3] = va[3]; vf[4] = vb[0]; vf[5] = vb[1]; vf[6] = vb[2]; vf[7] = vb[3];
;         vfr[df] = vf;
;       }
;       __builtin_amdgcn_s_setprio(1);
; #pragma unroll
;       for (int df = 0; df < 4; ++df)
; #pragma unroll
;         for (int r = 0; r < 2; ++r) O[df][r] = mfma16(vfr[df], Pf[r], O[df][r]);
;       __builtin_amdgcn_s_setprio(0);
.LBB0_391:
	v_sub_f32_e32 v139, v145, v138
	v_exp_f32_e32 v168, v139
	v_sub_f32_e32 v139, v144, v138
	v_exp_f32_e32 v169, v139
	v_sub_f32_e32 v139, v141, v138
	v_exp_f32_e32 v170, v139
	v_sub_f32_e32 v139, v140, v138
	v_exp_f32_e32 v171, v139
	v_sub_f32_e32 v139, v143, v138
	v_cvt_pk_bf16_f32 v164, v147, v149
	v_cvt_pk_bf16_f32 v165, v150, v148
	v_cvt_pk_bf16_f32 v166, v151, v146
	v_cvt_pk_bf16_f32 v167, v153, v152
	v_exp_f32_e32 v172, v139
	v_sub_f32_e32 v139, v142, v138
	s_cmp_lt_i32 s42, 0
	s_cbranch_scc1 .Lmy_lw_1
	v_mov_b32 v176, v179
	s_nop 0
	v_ashrrev_i32_e32 v202, 3, v176
	v_xor_b32_e32 v204, v202, v176
	v_lshlrev_b32_e32 v176, 3, v176
	v_lshlrev_b32_e32 v204, 4, v204
	v_and_b32_e32 v176, 56, v176
	v_lshlrev_b32_e32 v203, 7, v202
	v_and_b32_e32 v204, 0x70, v204
	v_mul_u32_u24_e32 v176, 0x88, v176
	v_lshlrev_b32_e32 v202, 1, v202
	v_add3_u32 v203, s64, v203, v204
	v_add3_u32 v176, s43, v176, v202
	s_waitcnt vmcnt(1)
	ds_write_b128 v203, v[64:67]
	s_waitcnt vmcnt(0)
	ds_write_b16 v176, v68 offset:16384
	ds_write_b16_d16_hi v176, v68 offset:16520
	ds_write_b16 v176, v69 offset:16656
	ds_write_b16_d16_hi v176, v69 offset:16792
	ds_write_b16 v176, v70 offset:16928
	ds_write_b16_d16_hi v176, v70 offset:17064
	ds_write_b16 v176, v71 offset:17200
	ds_write_b16_d16_hi v176, v71 offset:17336
.Lmy_lw_1:
	ds_read2_b64 v[140:143], v155 offset0:8 offset1:12
	ds_read2_b64 v[144:147], v156 offset0:24 offset1:28
	ds_read2_b64 v[148:151], v157 offset0:40 offset1:44
	ds_read2_b64 v[152:155], v158 offset0:56 offset1:60
	v_sub_f32_e32 v137, v137, v138
	v_sub_f32_e32 v136, v136, v138
	v_exp_f32_e32 v173, v139
	v_exp_f32_e32 v174, v137
	v_exp_f32_e32 v175, v136
	v_cvt_pk_bf16_f32 v198, v168, v169
	v_cvt_pk_bf16_f32 v199, v170, v171
	v_cvt_pk_bf16_f32 v200, v172, v173
	v_cvt_pk_bf16_f32 v201, v174, v175
	s_setprio 1
	s_waitcnt lgkmcnt(3)
	v_mfma_f32_16x16x32_bf16 v[136:139], v[140:143], v[164:167], v[116:119]
	v_mfma_f32_16x16x32_bf16 v[140:143], v[140:143], v[198:201], v[132:135]
	s_waitcnt lgkmcnt(2)
	v_mfma_f32_16x16x32_bf16 v[156:159], v[144:147], v[164:167], v[112:115]
	v_mfma_f32_16x16x32_bf16 v[144:147], v[144:147], v[198:201], v[128:131]
	s_waitcnt lgkmcnt(1)
	v_mfma_f32_16x16x32_bf16 v[160:163], v[148:151], v[164:167], v[108:111]
	v_mfma_f32_16x16x32_bf16 v[148:151], v[148:151], v[198:201], v[124:127]
	s_waitcnt lgkmcnt(0)
	v_mfma_f32_16x16x32_bf16 v[164:167], v[152:155], v[164:167], v[104:107]
	v_mfma_f32_16x16x32_bf16 v[152:155], v[152:155], v[198:201], v[120:123]
	s_setprio 0

; #define TIDX opaque_tid()
; __device__ __forceinline__ unsigned pk2(float lo, float hi) { const f32x2v v = {lo, hi}; const bf16x2v r = __builtin_convertvector(v, bf16x2v); return __builtin_bit_cast(unsigned, r); }
; __device__ __forceinline__ f32x4 mfma16(bf16x8 a, bf16x8 b, f32x4 c) { return __builtin_amdgcn_mfma_f32_16x16x32_bf16(a, b, c, 0, 0, 0); }
; __device__ __forceinline__ void kv_lwrite(const KVRegs& r, char* lds, int buf) {
;   const int tid = TIDX, row = tid >> 3, cq = tid & 7;
;   char* kt = lds + NSA_KT + buf * 8192 + row * 128;
;   *(u32x4*)(kt + ((cq ^ (row & 7)) << 4)) = r.k0;
;   bf16_t* vt = (bf16_t*)(lds + NSA_VT + buf * 8704) + (cq * 8) * 68 + row;
; #pragma unroll
;   for (int i = 0; i < 4; ++i) { vt[(2 * i) * 68] = (bf16_t)(r.v0[i] & 0xffffu); vt[(2 * i + 1) * 68] = (bf16_t)(r.v0[i] >> 16); }
; }
; template <int MODE>
; __device__ __forceinline__ void nsa_compute(int cur, int buf, int t, int hl, u64 mymask, const bf16x8 (&Qf)[2][2], f32x4 (&O)[4][2], float (&m)[2], float (&l)[2],
;                                             const float (&inv)[2], float* impw, char* lds) {
;     ...
;           for (int e = 0; e < 4; ++e) { pv[kk][e] = __builtin_amdgcn_exp2f(sv[kk][e] - me); ps += pv[kk][e]; }
;         l[r] += ps;
;       }
;       if (MODE != 0) {
;         const unsigned w0 = pk2(pv[0][0], pv[0][1]), w1 = pk2(pv[0][2], pv[0][3]), w2 = pk2(pv[1][0], pv[1][1]), w3 = pk2(pv[1][2], pv[1][3]);
;         u32x4 pw; pw.x = w0; pw.y = w1; pw.z = w2; pw.w = w3;
;         Pf[r] = __builtin_bit_cast(bf16x8, pw);
;       }
;     }
;     if (MODE != 0) {
;       bf16x8 vfr[4];
; #pragma unroll
;       for (int df = 0; df < 4; ++df) {
;         const bf16x4 va = *(const bf16x4*)(vt + (df * 16 + fr) * 68 + 32 * s2 + 4 * fq);
;         const bf16x4 vb = *(const bf16x4*)(vt + (df * 16 + fr) * 68 + 32 * s2 + 16 + 4 * fq);
;         bf16x8 vf; vf[0] = va[0]; vf[1] = va[1]; vf[2] = va[2]; vf[3] = va[3]; vf[4] = vb[0]; vf[5] = vb[1]; vf[6] = vb[2]; vf[7] = vb[3];
;         vfr[df] = vf;
;       }
;       __builtin_amdgcn_s_setprio(1);
; #pragma unroll
;       for (int df = 0; df < 4; ++df)
; #pragma unroll
;         for (int r = 0; r < 2; ++r) O[df][r] = mfma16(vfr[df], Pf[r], O[df][r]);
;       __builtin_amdgcn_s_setprio(0);
.LBB0_408:
	v_sub_f32_e32 v119, v199, v118
	v_exp_f32_e32 v175, v119
	v_sub_f32_e32 v119, v198, v118
	v_exp_f32_e32 v198, v119
	v_sub_f32_e32 v119, v173, v118
	v_exp_f32_e32 v173, v119
	v_sub_f32_e32 v119, v172, v118
	v_cvt_pk_bf16_f32 v208, v201, v203
	v_cvt_pk_bf16_f32 v209, v204, v202
	v_cvt_pk_bf16_f32 v210, v205, v200
	v_exp_f32_e32 v172, v119
	v_sub_f32_e32 v119, v240, v118
	s_cmp_lt_i32 s74, 0
	s_cbranch_scc1 .Lmy_lw_2
	v_mov_b32 v176, v179
	s_nop 0
	v_ashrrev_i32_e32 v230, 3, v176
	v_xor_b32_e32 v232, v230, v176
	v_lshlrev_b32_e32 v176, 3, v176
	v_lshlrev_b32_e32 v232, 4, v232
	v_and_b32_e32 v176, 56, v176
	v_lshlrev_b32_e32 v231, 7, v230
	v_and_b32_e32 v232, 0x70, v232
	v_mul_u32_u24_e32 v176, 0x88, v176
	v_lshlrev_b32_e32 v230, 1, v230
	v_add3_u32 v231, s71, v231, v232
	v_add3_u32 v176, s72, v176, v230
	s_waitcnt vmcnt(1)
	ds_write_b128 v231, v[48:51]
	s_waitcnt vmcnt(0)
	ds_write_b16 v176, v52 offset:16384
	ds_write_b16_d16_hi v176, v52 offset:16520
	ds_write_b16 v176, v53 offset:16656
	ds_write_b16_d16_hi v176, v53 offset:16792
	ds_write_b16 v176, v54 offset:16928
	ds_write_b16_d16_hi v176, v54 offset:17064
	ds_write_b16 v176, v55 offset:17200
	ds_write_b16_d16_hi v176, v55 offset:17336
.Lmy_lw_2:
	ds_read2_b64 v[202:205], v236 offset0:8 offset1:12
	ds_read2_b64 v[240:243], v237 offset0:24 offset1:28
	ds_read2_b64 v[244:247], v238 offset0:40 offset1:44
	ds_read2_b64 v[236:239], v239 offset0:56 offset1:60
	v_exp_f32_e32 v199, v119
	v_sub_f32_e32 v119, v174, v118
	v_sub_f32_e32 v117, v117, v118
	v_sub_f32_e32 v116, v116, v118
	v_exp_f32_e32 v174, v119
	v_exp_f32_e32 v200, v117
	v_exp_f32_e32 v201, v116
	v_cvt_pk_bf16_f32 v211, v207, v206
	v_cvt_pk_bf16_f32 v248, v175, v198
	v_cvt_pk_bf16_f32 v249, v173, v172
	v_cvt_pk_bf16_f32 v250, v199, v174
	v_cvt_pk_bf16_f32 v251, v200, v201
	s_setprio 1
	s_waitcnt lgkmcnt(3)
	v_mfma_f32_16x16x32_bf16 v[116:119], v[202:205], v[208:211], v[104:107]
	v_mfma_f32_16x16x32_bf16 v[104:107], v[202:205], v[248:251], v[124:127]
	s_waitcnt lgkmcnt(2)
	v_mfma_f32_16x16x32_bf16 v[124:127], v[240:243], v[208:211], v[108:111]
	v_mfma_f32_16x16x32_bf16 v[108:111], v[240:243], v[248:251], v[128:131]
	s_waitcnt lgkmcnt(1)
	v_mfma_f32_16x16x32_bf16 v[128:131], v[244:247], v[208:211], v[112:115]
	v_mfma_f32_16x16x32_bf16 v[112:115], v[244:247], v[248:251], v[132:135]
	s_waitcnt lgkmcnt(0)
	v_mfma_f32_16x16x32_bf16 v[132:135], v[236:239], v[208:211], v[120:123]
	v_mfma_f32_16x16x32_bf16 v[120:123], v[236:239], v[248:251], v[168:171]
	s_setprio 0

; #define TIDX opaque_tid()
; __device__ __forceinline__ unsigned pk2(float lo, float hi) { const f32x2v v = {lo, hi}; const bf16x2v r = __builtin_convertvector(v, bf16x2v); return __builtin_bit_cast(unsigned, r); }
; __device__ __forceinline__ f32x4 mfma16(bf16x8 a, bf16x8 b, f32x4 c) { return __builtin_amdgcn_mfma_f32_16x16x32_bf16(a, b, c, 0, 0, 0); }
; __device__ __forceinline__ void kv_lwrite(const KVRegs& r, char* lds, int buf) {
;   const int tid = TIDX, row = tid >> 3, cq = tid & 7;
;   char* kt = lds + NSA_KT + buf * 8192 + row * 128;
;   *(u32x4*)(kt + ((cq ^ (row & 7)) << 4)) = r.k0;
;   bf16_t* vt = (bf16_t*)(lds + NSA_VT + buf * 8704) + (cq * 8) * 68 + row;
; #pragma unroll
;   for (int i = 0; i < 4; ++i) { vt[(2 * i) * 68] = (bf16_t)(r.v0[i] & 0xffffu); vt[(2 * i + 1) * 68] = (bf16_t)(r.v0[i] >> 16); }
; }
; template <int MODE>
; __device__ __forceinline__ void nsa_compute(int cur, int buf, int t, int hl, u64 mymask, const bf16x8 (&Qf)[2][2], f32x4 (&O)[4][2], float (&m)[2], float (&l)[2],
;                                             const float (&inv)[2], float* impw, char* lds) {
;     ...
;           for (int e = 0; e < 4; ++e) { pv[kk][e] = __builtin_amdgcn_exp2f(sv[kk][e] - me); ps += pv[kk][e]; }
;         l[r] += ps;
;       }
;       if (MODE != 0) {
;         const unsigned w0 = pk2(pv[0][0], pv[0][1]), w1 = pk2(pv[0][2], pv[0][3]), w2 = pk2(pv[1][0], pv[1][1]), w3 = pk2(pv[1][2], pv[1][3]);
;         u32x4 pw; pw.x = w0; pw.y = w1; pw.z = w2; pw.w = w3;
;         Pf[r] = __builtin_bit_cast(bf16x8, pw);
;       }
;     }
;     if (MODE != 0) {
;       bf16x8 vfr[4];
; #pragma unroll
;       for (int df = 0; df < 4; ++df) {
;         const bf16x4 va = *(const bf16x4*)(vt + (df * 16 + fr) * 68 + 32 * s2 + 4 * fq);
;         const bf16x4 vb = *(const bf16x4*)(vt + (df * 16 + fr) * 68 + 32 * s2 + 16 + 4 * fq);
;         bf16x8 vf; vf[0] = va[0]; vf[1] = va[1]; vf[2] = va[2]; vf[3] = va[3]; vf[4] = vb[0]; vf[5] = vb[1]; vf[6] = vb[2]; vf[7] = vb[3];
;         vfr[df] = vf;
;       }
;       __builtin_amdgcn_s_setprio(1);
; #pragma unroll
;       for (int df = 0; df < 4; ++df)
; #pragma unroll
;         for (int r = 0; r < 2; ++r) O[df][r] = mfma16(vfr[df], Pf[r], O[df][r]);
;       __builtin_amdgcn_s_setprio(0);
.LBB0_448:
	v_cndmask_b32_e64 v91, v37, v228, s[36:37]
	v_cvt_pk_bf16_f32 v104, v47, v84
	v_cvt_pk_bf16_f32 v105, v85, v46
	v_cvt_pk_bf16_f32 v106, v87, v88
	v_cvt_pk_bf16_f32 v107, v89, v86
	v_sub_f32_e32 v37, v45, v91
	v_sub_f32_e32 v38, v44, v91
	s_xor_b32 s74, s74, 1
	s_cmp_lt_i32 s16, 0
	s_cbranch_scc1 .Lmy_lw_3
	v_mov_b32 v138, v179
	s_lshl_b32 s17, s74, 13
	v_ashrrev_i32_e32 v139, 3, v138
	v_xor_b32_e32 v141, v139, v138
	v_lshl_add_u32 v140, v139, 7, s17
	v_lshlrev_b32_e32 v141, 4, v141
	s_movk_i32 s30, 0x70
	v_lshlrev_b32_e32 v138, 3, v138
	v_and_or_b32 v140, v141, s30, v140
	s_lshl_b32 s30, s74, 9
	v_and_b32_e32 v138, 56, v138
	s_add_i32 s17, s17, s30
	v_mul_u32_u24_e32 v138, 0x88, v138
	v_lshlrev_b32_e32 v139, 1, v139
	v_add3_u32 v138, s17, v138, v139
	s_waitcnt vmcnt(1)
	ds_write_b128 v140, v[56:59]
	s_waitcnt vmcnt(0)
	ds_write_b16 v138, v60 offset:16384
	ds_write_b16_d16_hi v138, v60 offset:16520
	ds_write_b16 v138, v61 offset:16656
	ds_write_b16_d16_hi v138, v61 offset:16792
	ds_write_b16 v138, v62 offset:16928
	ds_write_b16_d16_hi v138, v62 offset:17064
	ds_write_b16 v138, v63 offset:17200
	ds_write_b16_d16_hi v138, v63 offset:17336
.Lmy_lw_3:
	ds_read2_b64 v[44:47], v94 offset0:8 offset1:12
	ds_read2_b64 v[84:87], v95 offset0:24 offset1:28
	ds_read2_b64 v[108:111], v96 offset0:40 offset1:44
	ds_read2_b64 v[112:115], v97 offset0:56 offset1:60
	v_sub_f32_e32 v39, v41, v91
	v_sub_f32_e32 v40, v40, v91
	v_sub_f32_e32 v41, v43, v91
	v_sub_f32_e32 v42, v42, v91
	v_sub_f32_e32 v43, v90, v91
	v_sub_f32_e32 v36, v36, v91
	v_exp_f32_e32 v37, v37
	v_exp_f32_e32 v38, v38
	v_exp_f32_e32 v39, v39
	v_exp_f32_e32 v40, v40
	v_exp_f32_e32 v41, v41
	v_exp_f32_e32 v42, v42
	v_exp_f32_e32 v43, v43
	v_exp_f32_e32 v36, v36
	v_cvt_pk_bf16_f32 v116, v37, v38
	v_cvt_pk_bf16_f32 v117, v39, v40
	v_cvt_pk_bf16_f32 v118, v41, v42
	v_cvt_pk_bf16_f32 v119, v43, v36
	s_setprio 1
	s_waitcnt lgkmcnt(3)
	v_mfma_f32_16x16x32_bf16 v[88:91], v[44:47], v[104:107], v[72:75]
	v_mfma_f32_16x16x32_bf16 v[96:99], v[44:47], v[116:119], v[80:83]
	s_waitcnt lgkmcnt(2)
	v_mfma_f32_16x16x32_bf16 v[100:103], v[84:87], v[104:107], v[24:27]
	v_mfma_f32_16x16x32_bf16 v[84:87], v[84:87], v[116:119], v[76:79]
	s_waitcnt lgkmcnt(1)
	v_mfma_f32_16x16x32_bf16 v[92:95], v[108:111], v[104:107], v[20:23]
	v_mfma_f32_16x16x32_bf16 v[76:79], v[108:111], v[116:119], v[32:35]
	s_waitcnt lgkmcnt(0)
	v_mfma_f32_16x16x32_bf16 v[80:83], v[112:115], v[104:107], v[16:19]
	v_mfma_f32_16x16x32_bf16 v[72:75], v[112:115], v[116:119], v[28:31]
	s_setprio 0

; #define TIDX opaque_tid()
; __device__ __forceinline__ unsigned pk2(float lo, float hi) { const f32x2v v = {lo, hi}; const bf16x2v r = __builtin_convertvector(v, bf16x2v); return __builtin_bit_cast(unsigned, r); }
; __device__ __forceinline__ f32x4 mfma16(bf16x8 a, bf16x8 b, f32x4 c) { return __builtin_amdgcn_mfma_f32_16x16x32_bf16(a, b, c, 0, 0, 0); }
; __device__ __forceinline__ void kv_lwrite(const KVRegs& r, char* lds, int buf) {
;   const int tid = TIDX, row = tid >> 3, cq = tid & 7;
;   char* kt = lds + NSA_KT + buf * 8192 + row * 128;
;   *(u32x4*)(kt + ((cq ^ (row & 7)) << 4)) = r.k0;
;   bf16_t* vt = (bf16_t*)(lds + NSA_VT + buf * 8704) + (cq * 8) * 68 + row;
; #pragma unroll
;   for (int i = 0; i < 4; ++i) { vt[(2 * i) * 68] = (bf16_t)(r.v0[i] & 0xffffu); vt[(2 * i + 1) * 68] = (bf16_t)(r.v0[i] >> 16); }
; }
; template <int MODE>
; __device__ __forceinline__ void nsa_compute(int cur, int buf, int t, int hl, u64 mymask, const bf16x8 (&Qf)[2][2], f32x4 (&O)[4][2], float (&m)[2], float (&l)[2],
;                                             const float (&inv)[2], float* impw, char* lds) {
;     ...
;           for (int e = 0; e < 4; ++e) { pv[kk][e] = __builtin_amdgcn_exp2f(sv[kk][e] - me); ps += pv[kk][e]; }
;         l[r] += ps;
;       }
;       if (MODE != 0) {
;         const unsigned w0 = pk2(pv[0][0], pv[0][1]), w1 = pk2(pv[0][2], pv[0][3]), w2 = pk2(pv[1][0], pv[1][1]), w3 = pk2(pv[1][2], pv[1][3]);
;         u32x4 pw; pw.x = w0; pw.y = w1; pw.z = w2; pw.w = w3;
;         Pf[r] = __builtin_bit_cast(bf16x8, pw);
;       }
;     }
;     if (MODE != 0) {
;       bf16x8 vfr[4];
; #pragma unroll
;       for (int df = 0; df < 4; ++df) {
;         const bf16x4 va = *(const bf16x4*)(vt + (df * 16 + fr) * 68 + 32 * s2 + 4 * fq);
;         const bf16x4 vb = *(const bf16x4*)(vt + (df * 16 + fr) * 68 + 32 * s2 + 16 + 4 * fq);
;         bf16x8 vf; vf[0] = va[0]; vf[1] = va[1]; vf[2] = va[2]; vf[3] = va[3]; vf[4] = vb[0]; vf[5] = vb[1]; vf[6] = vb[2]; vf[7] = vb[3];
;         vfr[df] = vf;
;       }
;       __builtin_amdgcn_s_setprio(1);
; #pragma unroll
;       for (int df = 0; df < 4; ++df)
; #pragma unroll
;         for (int r = 0; r < 2; ++r) O[df][r] = mfma16(vfr[df], Pf[r], O[df][r]);
;       __builtin_amdgcn_s_setprio(0);
.LBB0_465:
	v_cndmask_b32_e64 v106, v106, v228, s[36:37]
	v_sub_f32_e32 v107, v113, v106
	v_exp_f32_e32 v136, v107
	v_sub_f32_e32 v107, v112, v106
	v_exp_f32_e32 v137, v107
	v_sub_f32_e32 v107, v109, v106
	v_exp_f32_e32 v138, v107
	v_sub_f32_e32 v107, v108, v106
	v_exp_f32_e32 v139, v107
	v_sub_f32_e32 v107, v111, v106
	v_cvt_pk_bf16_f32 v132, v115, v116
	v_cvt_pk_bf16_f32 v133, v117, v114
	v_cvt_pk_bf16_f32 v134, v119, v120
	v_cvt_pk_bf16_f32 v135, v121, v118
	v_exp_f32_e32 v140, v107
	v_sub_f32_e32 v107, v110, v106
	s_cmp_lt_i32 s62, 0
	s_cbranch_scc1 .Lmy_lw_4
	v_mov_b32 v152, v179
	s_nop 0
	v_ashrrev_i32_e32 v153, 3, v152
	v_xor_b32_e32 v155, v153, v152
	v_lshlrev_b32_e32 v152, 3, v152
	v_lshlrev_b32_e32 v155, 4, v155
	v_and_b32_e32 v152, 56, v152
	v_lshlrev_b32_e32 v154, 7, v153
	v_and_b32_e32 v155, 0x70, v155
	v_mul_u32_u24_e32 v152, 0x88, v152
	v_lshlrev_b32_e32 v153, 1, v153
	v_add3_u32 v154, s63, v154, v155
	v_add3_u32 v152, s71, v152, v153
	s_waitcnt vmcnt(1)
	ds_write_b128 v154, v[64:67]
	s_waitcnt vmcnt(0)
	ds_write_b16 v152, v68 offset:16384
	ds_write_b16_d16_hi v152, v68 offset:16520
	ds_write_b16 v152, v69 offset:16656
	ds_write_b16_d16_hi v152, v69 offset:16792
	ds_write_b16 v152, v70 offset:16928
	ds_write_b16_d16_hi v152, v70 offset:17064
	ds_write_b16 v152, v71 offset:17200
	ds_write_b16_d16_hi v152, v71 offset:17336
.Lmy_lw_4:
	ds_read2_b64 v[108:111], v123 offset0:8 offset1:12
	ds_read2_b64 v[112:115], v124 offset0:24 offset1:28
	ds_read2_b64 v[116:119], v125 offset0:40 offset1:44
	ds_read2_b64 v[120:123], v126 offset0:56 offset1:60
	v_sub_f32_e32 v105, v105, v106
	v_sub_f32_e32 v104, v104, v106
	v_exp_f32_e32 v141, v107
	v_exp_f32_e32 v142, v105
	v_exp_f32_e32 v143, v104
	v_cvt_pk_bf16_f32 v148, v136, v137
	v_cvt_pk_bf16_f32 v149, v138, v139
	v_cvt_pk_bf16_f32 v150, v140, v141
	v_cvt_pk_bf16_f32 v151, v142, v143
	s_setprio 1
	s_waitcnt lgkmcnt(3)
	v_mfma_f32_16x16x32_bf16 v[104:107], v[108:111], v[132:135], v[28:31]
	v_mfma_f32_16x16x32_bf16 v[108:111], v[108:111], v[148:151], v[44:47]
	s_waitcnt lgkmcnt(2)
	v_mfma_f32_16x16x32_bf16 v[124:127], v[112:115], v[132:135], v[24:27]
	v_mfma_f32_16x16x32_bf16 v[112:115], v[112:115], v[148:151], v[40:43]
	s_waitcnt lgkmcnt(1)
	v_mfma_f32_16x16x32_bf16 v[128:131], v[116:119], v[132:135], v[20:23]
	v_mfma_f32_16x16x32_bf16 v[116:119], v[116:119], v[148:151], v[36:39]
	s_waitcnt lgkmcnt(0)
	v_mfma_f32_16x16x32_bf16 v[132:135], v[120:123], v[132:135], v[16:19]
	v_mfma_f32_16x16x32_bf16 v[120:123], v[120:123], v[148:151], v[32:35]
	s_setprio 0

; #define TIDX opaque_tid()
; __device__ __forceinline__ unsigned pk2(float lo, float hi) { const f32x2v v = {lo, hi}; const bf16x2v r = __builtin_convertvector(v, bf16x2v); return __builtin_bit_cast(unsigned, r); }
; __device__ __forceinline__ f32x4 mfma16(bf16x8 a, bf16x8 b, f32x4 c) { return __builtin_amdgcn_mfma_f32_16x16x32_bf16(a, b, c, 0, 0, 0); }
; __device__ __forceinline__ void kv_lwrite(const KVRegs& r, char* lds, int buf) {
;   const int tid = TIDX, row = tid >> 3, cq = tid & 7;
;   char* kt = lds + NSA_KT + buf * 8192 + row * 128;
;   *(u32x4*)(kt + ((cq ^ (row & 7)) << 4)) = r.k0;
;   bf16_t* vt = (bf16_t*)(lds + NSA_VT + buf * 8704) + (cq * 8) * 68 + row;
; #pragma unroll
;   for (int i = 0; i < 4; ++i) { vt[(2 * i) * 68] = (bf16_t)(r.v0[i] & 0xffffu); vt[(2 * i + 1) * 68] = (bf16_t)(r.v0[i] >> 16); }
; }
; template <int MODE>
; __device__ __forceinline__ void nsa_compute(int cur, int buf, int t, int hl, u64 mymask, const bf16x8 (&Qf)[2][2], f32x4 (&O)[4][2], float (&m)[2], float (&l)[2],
;                                             const float (&inv)[2], float* impw, char* lds) {
;     ...
;           for (int e = 0; e < 4; ++e) { pv[kk][e] = __builtin_amdgcn_exp2f(sv[kk][e] - me); ps += pv[kk][e]; }
;         l[r] += ps;
;       }
;       if (MODE != 0) {
;         const unsigned w0 = pk2(pv[0][0], pv[0][1]), w1 = pk2(pv[0][2], pv[0][3]), w2 = pk2(pv[1][0], pv[1][1]), w3 = pk2(pv[1][2], pv[1][3]);
;         u32x4 pw; pw.x = w0; pw.y = w1; pw.z = w2; pw.w = w3;
;         Pf[r] = __builtin_bit_cast(bf16x8, pw);
;       }
;     }
;     if (MODE != 0) {
;       bf16x8 vfr[4];
; #pragma unroll
;       for (int df = 0; df < 4; ++df) {
;         const bf16x4 va = *(const bf16x4*)(vt + (df * 16 + fr) * 68 + 32 * s2 + 4 * fq);
;         const bf16x4 vb = *(const bf16x4*)(vt + (df * 16 + fr) * 68 + 32 * s2 + 16 + 4 * fq);
;         bf16x8 vf; vf[0] = va[0]; vf[1] = va[1]; vf[2] = va[2]; vf[3] = va[3]; vf[4] = vb[0]; vf[5] = vb[1]; vf[6] = vb[2]; vf[7] = vb[3];
;         vfr[df] = vf;
;       }
;       __builtin_amdgcn_s_setprio(1);
; #pragma unroll
;       for (int df = 0; df < 4; ++df)
; #pragma unroll
;         for (int r = 0; r < 2; ++r) O[df][r] = mfma16(vfr[df], Pf[r], O[df][r]);
;       __builtin_amdgcn_s_setprio(0);
.LBB0_482:
	v_cndmask_b32_e64 v163, v137, v228, s[36:37]
	v_cvt_pk_bf16_f32 v164, v151, v152
	v_cvt_pk_bf16_f32 v165, v153, v150
	v_cvt_pk_bf16_f32 v166, v155, v156
	v_cvt_pk_bf16_f32 v167, v157, v154
	v_sub_f32_e32 v137, v149, v163
	v_sub_f32_e32 v138, v148, v163
	v_sub_f32_e32 v139, v141, v163
	v_sub_f32_e32 v140, v140, v163
	v_sub_f32_e32 v141, v143, v163
	v_sub_f32_e32 v142, v142, v163
	v_sub_f32_e32 v143, v158, v163
	v_sub_f32_e32 v136, v136, v163
	s_cmp_lt_i32 s75, 0
	s_cbranch_scc1 .Lmy_lw_5
	v_mov_b32 v172, v179
	s_nop 0
	v_ashrrev_i32_e32 v173, 3, v172
	v_xor_b32_e32 v175, v173, v172
	v_lshlrev_b32_e32 v172, 3, v172
	v_lshlrev_b32_e32 v175, 4, v175
	v_and_b32_e32 v172, 56, v172
	v_lshlrev_b32_e32 v174, 7, v173
	v_and_b32_e32 v175, 0x70, v175
	v_mul_u32_u24_e32 v172, 0x88, v172
	v_lshlrev_b32_e32 v173, 1, v173
	v_add3_u32 v174, s72, v174, v175
	v_add3_u32 v172, s73, v172, v173
	s_waitcnt vmcnt(1)
	ds_write_b128 v174, v[48:51]
	s_waitcnt vmcnt(0)
	ds_write_b16 v172, v52 offset:16384
	ds_write_b16_d16_hi v172, v52 offset:16520
	ds_write_b16 v172, v53 offset:16656
	ds_write_b16_d16_hi v172, v53 offset:16792
	ds_write_b16 v172, v54 offset:16928
	ds_write_b16_d16_hi v172, v54 offset:17064
	ds_write_b16 v172, v55 offset:17200
	ds_write_b16_d16_hi v172, v55 offset:17336
.Lmy_lw_5:
	ds_read2_b64 v[148:151], v159 offset0:8 offset1:12
	ds_read2_b64 v[152:155], v160 offset0:24 offset1:28
	ds_read2_b64 v[156:159], v161 offset0:40 offset1:44
	ds_read2_b64 v[160:163], v162 offset0:56 offset1:60
	v_exp_f32_e32 v137, v137
	v_exp_f32_e32 v138, v138
	v_exp_f32_e32 v139, v139
	v_exp_f32_e32 v140, v140
	v_exp_f32_e32 v141, v141
	v_exp_f32_e32 v142, v142
	v_exp_f32_e32 v143, v143
	v_exp_f32_e32 v136, v136
	v_cvt_pk_bf16_f32 v168, v137, v138
	v_cvt_pk_bf16_f32 v169, v139, v140
	v_cvt_pk_bf16_f32 v170, v141, v142
	v_cvt_pk_bf16_f32 v171, v143, v136
	s_setprio 1
	s_waitcnt lgkmcnt(3)
	v_mfma_f32_16x16x32_bf16 v[16:19], v[148:151], v[164:167], v[16:19]
	v_mfma_f32_16x16x32_bf16 v[20:23], v[148:151], v[168:171], v[20:23]
	s_waitcnt lgkmcnt(2)
	v_mfma_f32_16x16x32_bf16 v[24:27], v[152:155], v[164:167], v[24:27]
	v_mfma_f32_16x16x32_bf16 v[28:31], v[152:155], v[168:171], v[28:31]
	s_waitcnt lgkmcnt(1)
	v_mfma_f32_16x16x32_bf16 v[32:35], v[156:159], v[164:167], v[32:35]
	v_mfma_f32_16x16x32_bf16 v[36:39], v[156:159], v[168:171], v[36:39]
	s_waitcnt lgkmcnt(0)
	v_mfma_f32_16x16x32_bf16 v[40:43], v[160:163], v[164:167], v[40:43]
	v_mfma_f32_16x16x32_bf16 v[44:47], v[160:163], v[168:171], v[44:47]
	s_setprio 0
